# P6 epilogue residual stores issued at agent scope (write-through) so the phase-end L2 writeback has less to flush; on v61
# speedup vs baseline: 1.0064x; 1.0064x over previous
;     __device__ __forceinline__ void operator()(const f32x4 (&acc)[2][2][4][2], const pg8::Unit& u, int wr, int wc, int fr, int fq) const {
;         const int row0 = u.pm * 256 + wr * 64 + fr, col0 = u.pn * 256 + wc * 32 + 4 * fq;
;         const float* gp = gate + (size_t)((u.pm * 256) / SEQ) * MODLD + col0;
;         f32x4 gv[2][2];
; #pragma unroll
;         for (int bj = 0; bj < 2; ++bj)
; #pragma unroll
;             for (int n = 0; n < 2; ++n) gv[bj][n] = *(const f32x4*)(gp + bj * 128 + n * 16);
; #pragma unroll
;         for (int ai = 0; ai < 2; ++ai)
; #pragma unroll
;             for (int m = 0; m < 4; ++m) { const size_t off = (size_t)(row0 + ai * 128 + m * 16) * ldc + col0;
; #pragma unroll
;                 for (int bj = 0; bj < 2; ++bj)
; #pragma unroll
;                     for (int n = 0; n < 2; ++n) { const f32x4 b = *(const f32x4*)(base + off + bj * 128 + n * 16); *(f32x4*)(out + off + bj * 128 + n * 16) = b + gv[bj][n] * acc[ai][bj][m][n]; }
;                 asm volatile("" ::: "memory"); }
;     }
.LBB0_656:
	s_ashr_i32 s11, s16, 31
	v_lshl_add_u32 v172, s16, 8, v174
	v_lshl_or_b32 v170, s17, 8, v176
	s_lshr_b32 s11, s11, 29
	v_ashrrev_i32_e32 v173, 31, v172
	s_add_i32 s11, s16, s11
	v_ashrrev_i32_e32 v171, 31, v170
	v_lshlrev_b64 v[168:169], 11, v[172:173]
	s_ashr_i32 s11, s11, 3
	v_lshl_add_u64 v[168:169], v[168:169], 0, v[170:171]
	v_mad_i64_i32 v[120:121], s[18:19], s11, v193, v[158:159]
	v_lshlrev_b64 v[168:169], 2, v[168:169]
	v_lshl_add_u64 v[120:121], v[170:171], 2, v[120:121]
	s_waitcnt vmcnt(0)
	v_lshl_add_u64 v[170:171], v[146:147], 0, v[168:169]
	v_lshl_add_u64 v[172:173], v[144:145], 0, v[168:169]
	global_load_dwordx4 v[136:139], v[120:121], off
	global_load_dwordx4 v[132:135], v[120:121], off offset:64
	global_load_dwordx4 v[128:131], v[120:121], off offset:512
	s_nop 0
	global_load_dwordx4 v[120:123], v[120:121], off offset:576
	s_mov_b64 s[16:17], 0x0
	v_lshl_add_u64 v[178:179], v[170:171], 0, s[16:17]
	global_load_dwordx4 v[200:203], v[178:179], off
	global_load_dwordx4 v[204:207], v[178:179], off offset:64
	global_load_dwordx4 v[208:211], v[178:179], off offset:512
	global_load_dwordx4 v[212:215], v[178:179], off offset:576
	s_mov_b64 s[16:17], 0x20000
	v_lshl_add_u64 v[178:179], v[170:171], 0, s[16:17]
	global_load_dwordx4 v[216:219], v[178:179], off
	global_load_dwordx4 v[220:223], v[178:179], off offset:64
	global_load_dwordx4 v[224:227], v[178:179], off offset:512
	global_load_dwordx4 v[228:231], v[178:179], off offset:576
	s_mov_b64 s[16:17], 0x40000
	v_lshl_add_u64 v[178:179], v[170:171], 0, s[16:17]
	global_load_dwordx4 v[232:235], v[178:179], off
	global_load_dwordx4 v[236:239], v[178:179], off offset:64
	global_load_dwordx4 v[182:185], v[178:179], off offset:512
	global_load_dwordx4 v[186:189], v[178:179], off offset:576
	s_waitcnt vmcnt(8)
	s_mov_b64 s[16:17], 0x0
	v_lshl_add_u64 v[180:181], v[172:173], 0, s[16:17]
	v_pk_fma_f32 v[142:143], v[142:143], v[138:139], v[202:203]
	v_pk_fma_f32 v[140:141], v[140:141], v[136:137], v[200:201]
	v_pk_fma_f32 v[126:127], v[126:127], v[134:135], v[206:207]
	v_pk_fma_f32 v[124:125], v[124:125], v[132:133], v[204:205]
	v_pk_fma_f32 v[118:119], v[118:119], v[130:131], v[210:211]
	v_pk_fma_f32 v[116:117], v[116:117], v[128:129], v[208:209]
	v_pk_fma_f32 v[114:115], v[114:115], v[122:123], v[214:215]
	v_pk_fma_f32 v[112:113], v[112:113], v[120:121], v[212:213]
	global_store_dwordx4 v[180:181], v[140:143], off sc1
	global_store_dwordx4 v[180:181], v[124:127], off offset:64 sc1
	global_store_dwordx4 v[180:181], v[116:119], off offset:512 sc1
	global_store_dwordx4 v[180:181], v[112:115], off offset:576 sc1
	s_mov_b64 s[16:17], 0x60000
	v_lshl_add_u64 v[178:179], v[170:171], 0, s[16:17]
	global_load_dwordx4 v[200:203], v[178:179], off
	global_load_dwordx4 v[204:207], v[178:179], off offset:64
	global_load_dwordx4 v[208:211], v[178:179], off offset:512
	global_load_dwordx4 v[212:215], v[178:179], off offset:576
	s_waitcnt vmcnt(12)
	s_mov_b64 s[16:17], 0x20000
	v_lshl_add_u64 v[180:181], v[172:173], 0, s[16:17]
	v_pk_fma_f32 v[110:111], v[110:111], v[138:139], v[218:219]
	v_pk_fma_f32 v[108:109], v[108:109], v[136:137], v[216:217]
	v_pk_fma_f32 v[106:107], v[106:107], v[134:135], v[222:223]
	v_pk_fma_f32 v[104:105], v[104:105], v[132:133], v[220:221]
	v_pk_fma_f32 v[102:103], v[102:103], v[130:131], v[226:227]
	v_pk_fma_f32 v[100:101], v[100:101], v[128:129], v[224:225]
	v_pk_fma_f32 v[98:99], v[98:99], v[122:123], v[230:231]
	v_pk_fma_f32 v[96:97], v[96:97], v[120:121], v[228:229]
	global_store_dwordx4 v[180:181], v[108:111], off sc1
	global_store_dwordx4 v[180:181], v[104:107], off offset:64 sc1
	global_store_dwordx4 v[180:181], v[100:103], off offset:512 sc1
	global_store_dwordx4 v[180:181], v[96:99], off offset:576 sc1
	s_mov_b64 s[16:17], 0x100000
	v_lshl_add_u64 v[178:179], v[170:171], 0, s[16:17]
	global_load_dwordx4 v[216:219], v[178:179], off
	global_load_dwordx4 v[220:223], v[178:179], off offset:64
	global_load_dwordx4 v[224:227], v[178:179], off offset:512
	global_load_dwordx4 v[228:231], v[178:179], off offset:576
	s_waitcnt vmcnt(16)
	s_mov_b64 s[16:17], 0x40000
	v_lshl_add_u64 v[180:181], v[172:173], 0, s[16:17]
	v_pk_fma_f32 v[94:95], v[94:95], v[138:139], v[234:235]
	v_pk_fma_f32 v[92:93], v[92:93], v[136:137], v[232:233]
	v_pk_fma_f32 v[90:91], v[90:91], v[134:135], v[238:239]
	v_pk_fma_f32 v[88:89], v[88:89], v[132:133], v[236:237]
	v_pk_fma_f32 v[86:87], v[86:87], v[130:131], v[184:185]
	v_pk_fma_f32 v[84:85], v[84:85], v[128:129], v[182:183]
	v_pk_fma_f32 v[82:83], v[82:83], v[122:123], v[188:189]
	v_pk_fma_f32 v[80:81], v[80:81], v[120:121], v[186:187]
	global_store_dwordx4 v[180:181], v[92:95], off sc1
	global_store_dwordx4 v[180:181], v[88:91], off offset:64 sc1
	global_store_dwordx4 v[180:181], v[84:87], off offset:512 sc1
	global_store_dwordx4 v[180:181], v[80:83], off offset:576 sc1
	s_mov_b64 s[16:17], 0x120000
	v_lshl_add_u64 v[178:179], v[170:171], 0, s[16:17]
	global_load_dwordx4 v[232:235], v[178:179], off
	global_load_dwordx4 v[236:239], v[178:179], off offset:64
	global_load_dwordx4 v[182:185], v[178:179], off offset:512
	global_load_dwordx4 v[186:189], v[178:179], off offset:576
	s_waitcnt vmcnt(16)
;     __device__ __forceinline__ void operator()(const f32x4 (&acc)[2][2][4][2], const pg8::Unit& u, int wr, int wc, int fr, int fq) const {
;     ...
;         for (int ai = 0; ai < 2; ++ai)
; #pragma unroll
;             for (int m = 0; m < 4; ++m) { const size_t off = (size_t)(row0 + ai * 128 + m * 16) * ldc + col0;
; #pragma unroll
;                 for (int bj = 0; bj < 2; ++bj)
; #pragma unroll
;                     for (int n = 0; n < 2; ++n) { const f32x4 b = *(const f32x4*)(base + off + bj * 128 + n * 16); *(f32x4*)(out + off + bj * 128 + n * 16) = b + gv[bj][n] * acc[ai][bj][m][n]; }
;                 asm volatile("" ::: "memory"); }
;     }
	s_mov_b64 s[16:17], 0x60000
	v_lshl_add_u64 v[180:181], v[172:173], 0, s[16:17]
	v_pk_fma_f32 v[78:79], v[78:79], v[138:139], v[202:203]
	v_pk_fma_f32 v[76:77], v[76:77], v[136:137], v[200:201]
	v_pk_fma_f32 v[74:75], v[74:75], v[134:135], v[206:207]
	v_pk_fma_f32 v[72:73], v[72:73], v[132:133], v[204:205]
	v_pk_fma_f32 v[70:71], v[70:71], v[130:131], v[210:211]
	v_pk_fma_f32 v[68:69], v[68:69], v[128:129], v[208:209]
	v_pk_fma_f32 v[66:67], v[66:67], v[122:123], v[214:215]
	v_pk_fma_f32 v[64:65], v[64:65], v[120:121], v[212:213]
	global_store_dwordx4 v[180:181], v[76:79], off sc1
	global_store_dwordx4 v[180:181], v[72:75], off offset:64 sc1
	global_store_dwordx4 v[180:181], v[68:71], off offset:512 sc1
	global_store_dwordx4 v[180:181], v[64:67], off offset:576 sc1
	s_mov_b64 s[16:17], 0x140000
	v_lshl_add_u64 v[178:179], v[170:171], 0, s[16:17]
	global_load_dwordx4 v[200:203], v[178:179], off
	global_load_dwordx4 v[204:207], v[178:179], off offset:64
	global_load_dwordx4 v[208:211], v[178:179], off offset:512
	global_load_dwordx4 v[212:215], v[178:179], off offset:576
	s_waitcnt vmcnt(16)
	s_mov_b64 s[16:17], 0x100000
	v_lshl_add_u64 v[180:181], v[172:173], 0, s[16:17]
	v_pk_fma_f32 v[62:63], v[62:63], v[138:139], v[218:219]
	v_pk_fma_f32 v[60:61], v[60:61], v[136:137], v[216:217]
	v_pk_fma_f32 v[58:59], v[58:59], v[134:135], v[222:223]
	v_pk_fma_f32 v[56:57], v[56:57], v[132:133], v[220:221]
	v_pk_fma_f32 v[54:55], v[54:55], v[130:131], v[226:227]
	v_pk_fma_f32 v[52:53], v[52:53], v[128:129], v[224:225]
	v_pk_fma_f32 v[50:51], v[50:51], v[122:123], v[230:231]
	v_pk_fma_f32 v[48:49], v[48:49], v[120:121], v[228:229]
	global_store_dwordx4 v[180:181], v[60:63], off sc1
	global_store_dwordx4 v[180:181], v[56:59], off offset:64 sc1
	global_store_dwordx4 v[180:181], v[52:55], off offset:512 sc1
	global_store_dwordx4 v[180:181], v[48:51], off offset:576 sc1
	s_mov_b64 s[16:17], 0x160000
	v_lshl_add_u64 v[178:179], v[170:171], 0, s[16:17]
	global_load_dwordx4 v[216:219], v[178:179], off
	global_load_dwordx4 v[220:223], v[178:179], off offset:64
	global_load_dwordx4 v[224:227], v[178:179], off offset:512
	global_load_dwordx4 v[228:231], v[178:179], off offset:576
	s_waitcnt vmcnt(16)
	s_mov_b64 s[16:17], 0x120000
	v_lshl_add_u64 v[180:181], v[172:173], 0, s[16:17]
	v_pk_fma_f32 v[46:47], v[46:47], v[138:139], v[234:235]
	v_pk_fma_f32 v[44:45], v[44:45], v[136:137], v[232:233]
	v_pk_fma_f32 v[42:43], v[42:43], v[134:135], v[238:239]
	v_pk_fma_f32 v[40:41], v[40:41], v[132:133], v[236:237]
	v_pk_fma_f32 v[38:39], v[38:39], v[130:131], v[184:185]
	v_pk_fma_f32 v[36:37], v[36:37], v[128:129], v[182:183]
	v_pk_fma_f32 v[34:35], v[34:35], v[122:123], v[188:189]
	v_pk_fma_f32 v[32:33], v[32:33], v[120:121], v[186:187]
	global_store_dwordx4 v[180:181], v[44:47], off sc1
	global_store_dwordx4 v[180:181], v[40:43], off offset:64 sc1
	global_store_dwordx4 v[180:181], v[36:39], off offset:512 sc1
	global_store_dwordx4 v[180:181], v[32:35], off offset:576 sc1
	s_waitcnt vmcnt(12)
	s_mov_b64 s[16:17], 0x140000
	v_lshl_add_u64 v[180:181], v[172:173], 0, s[16:17]
	v_pk_fma_f32 v[30:31], v[30:31], v[138:139], v[202:203]
	v_pk_fma_f32 v[28:29], v[28:29], v[136:137], v[200:201]
	v_pk_fma_f32 v[26:27], v[26:27], v[134:135], v[206:207]
	v_pk_fma_f32 v[24:25], v[24:25], v[132:133], v[204:205]
	v_pk_fma_f32 v[22:23], v[22:23], v[130:131], v[210:211]
	v_pk_fma_f32 v[20:21], v[20:21], v[128:129], v[208:209]
	v_pk_fma_f32 v[18:19], v[18:19], v[122:123], v[214:215]
	v_pk_fma_f32 v[16:17], v[16:17], v[120:121], v[212:213]
	global_store_dwordx4 v[180:181], v[28:31], off sc1
	global_store_dwordx4 v[180:181], v[24:27], off offset:64 sc1
	global_store_dwordx4 v[180:181], v[20:23], off offset:512 sc1
	global_store_dwordx4 v[180:181], v[16:19], off offset:576 sc1
	s_waitcnt vmcnt(8)
	s_mov_b64 s[16:17], 0x160000
	v_lshl_add_u64 v[180:181], v[172:173], 0, s[16:17]
	v_pk_fma_f32 v[14:15], v[14:15], v[138:139], v[218:219]
	v_pk_fma_f32 v[12:13], v[12:13], v[136:137], v[216:217]
	v_pk_fma_f32 v[10:11], v[10:11], v[134:135], v[222:223]
	v_pk_fma_f32 v[8:9], v[8:9], v[132:133], v[220:221]
	v_pk_fma_f32 v[6:7], v[6:7], v[130:131], v[226:227]
	v_pk_fma_f32 v[4:5], v[4:5], v[128:129], v[224:225]
	v_pk_fma_f32 v[2:3], v[2:3], v[122:123], v[230:231]
	v_pk_fma_f32 v[0:1], v[0:1], v[120:121], v[228:229]
	global_store_dwordx4 v[180:181], v[12:15], off sc1
	global_store_dwordx4 v[180:181], v[8:11], off offset:64 sc1
	global_store_dwordx4 v[180:181], v[4:7], off offset:512 sc1
	global_store_dwordx4 v[180:181], v[0:3], off offset:576 sc1
	s_mov_b64 s[16:17], -1
	s_andn2_b64 vcc, exec, s[4:5]
	s_cbranch_vccnz .LBB0_645
	s_andn2_b64 vcc, exec, s[6:7]
	s_cbranch_vccnz .LBB0_644
	s_barrier
	s_branch .LBB0_644
